# P0: weight-conversion items given only to workgroups that do not run the adaLN GEMV (48 adaLN workgroups were the phase critical path)
# speedup vs baseline: 1.0936x; 1.0096x over previous
.LBB0_28:
	s_waitcnt lgkmcnt(0)
	v_writelane_b32 v241, s44, 17
	s_movk_i32 s4, 0x2880
	v_lshlrev_b32_e32 v24, 6, v23
	v_writelane_b32 v241, s45, 18
	v_writelane_b32 v241, s46, 19
	v_writelane_b32 v241, s47, 20
	v_writelane_b32 v241, s48, 21
	v_writelane_b32 v241, s49, 22
	v_writelane_b32 v241, s50, 23
	v_writelane_b32 v241, s51, 24
	v_writelane_b32 v241, s52, 25
	v_writelane_b32 v241, s53, 26
	v_writelane_b32 v241, s54, 27
	v_writelane_b32 v241, s55, 28
	v_writelane_b32 v241, s56, 29
	v_writelane_b32 v241, s57, 30
	v_writelane_b32 v241, s58, 31
	v_writelane_b32 v241, s59, 32
	s_load_dwordx16 s[36:51], s[0:1], 0x40
	s_load_dwordx16 s[52:67], s[0:1], 0x178
	s_waitcnt lgkmcnt(0)
	v_writelane_b32 v241, s36, 33
	s_nop 1
	v_writelane_b32 v241, s37, 34
	v_writelane_b32 v241, s38, 35
	v_writelane_b32 v241, s39, 36
	v_writelane_b32 v241, s40, 37
	v_writelane_b32 v241, s41, 38
	v_writelane_b32 v241, s42, 39
	v_writelane_b32 v241, s43, 40
	v_writelane_b32 v241, s44, 41
	v_writelane_b32 v241, s45, 42
	v_writelane_b32 v241, s46, 43
	v_writelane_b32 v241, s47, 44
	v_writelane_b32 v241, s48, 45
	v_writelane_b32 v241, s49, 46
	v_writelane_b32 v241, s50, 47
	v_writelane_b32 v241, s51, 48
	s_load_dwordx16 s[36:51], s[0:1], 0x80
	s_waitcnt lgkmcnt(0)
	v_writelane_b32 v241, s36, 49
	s_nop 1
	v_writelane_b32 v241, s37, 50
	v_writelane_b32 v241, s38, 51
	v_writelane_b32 v241, s39, 52
	v_writelane_b32 v241, s40, 53
	v_writelane_b32 v241, s41, 54
	v_writelane_b32 v241, s42, 55
	v_writelane_b32 v241, s43, 56
	v_writelane_b32 v241, s44, 57
	v_writelane_b32 v241, s45, 58
	v_writelane_b32 v241, s46, 59
	v_writelane_b32 v241, s47, 60
	v_writelane_b32 v241, s48, 61
	v_writelane_b32 v241, s49, 62
	v_writelane_b32 v241, s50, 63
	v_writelane_b32 v240, s51, 0
	s_load_dwordx16 s[36:51], s[0:1], 0x130
	v_readlane_b32 s2, v241, 1
	v_readlane_b32 s3, v241, 2
	s_load_dword s0, s[2:3], 0x10
	s_nop 0
	s_load_dword s2, s[2:3], 0x0
	s_lshl_b32 s1, s90, 3
	s_waitcnt lgkmcnt(0)
	v_writelane_b32 v240, s36, 1
	v_writelane_b32 v241, s1, 16
	s_lshr_b32 s0, s0, 16
	v_writelane_b32 v240, s37, 2
	v_writelane_b32 v240, s38, 3
	v_writelane_b32 v240, s39, 4
	v_writelane_b32 v240, s40, 5
	v_writelane_b32 v240, s41, 6
	v_writelane_b32 v240, s42, 7
	v_writelane_b32 v240, s43, 8
	v_writelane_b32 v240, s44, 9
	v_writelane_b32 v240, s45, 10
	v_writelane_b32 v240, s46, 11
	s_cmp_lg_u32 s0, 0
	v_writelane_b32 v240, s47, 12
	v_add_u32_e32 v22, s1, v23
	s_cselect_b64 s[0:1], -1, 0
	v_writelane_b32 v240, s48, 13
	s_cmp_lg_u64 s[0:1], 0
	v_writelane_b32 v240, s49, 14
	s_addc_u32 s2, s2, 0
	v_writelane_b32 v240, s50, 15
	s_lshl_b32 s3, s2, 3
	s_mov_b32 s100, s90
	s_cmp_lt_u32 s2, 97
	s_cbranch_scc1 .Lp0_bal_done
	s_sub_i32 s100, s90, 48
	s_sub_i32 s3, s2, 48
	s_lshl_b32 s3, s3, 3
	s_lshl_b32 s101, s100, 3
	v_add_u32_e32 v22, s101, v23
	s_cmp_lt_i32 s90, 48
	s_cbranch_scc0 .Lp0_bal_done
	v_mov_b32_e32 v22, 0x3fffffff
.Lp0_bal_done:
	v_cmp_gt_i32_e32 vcc, s4, v22
	v_writelane_b32 v240, s51, 16
	s_and_saveexec_b64 s[0:1], vcc
	s_cbranch_execz .LBB0_33
	v_lshl_add_u32 v0, s100, 9, v24
	v_or_b32_e32 v0, v0, v142
	s_lshl_b32 s8, s3, 6
	s_mov_b64 s[4:5], 0
	v_mov_b32_e32 v1, v22
	s_movk_i32 s9, 0x5080
	s_branch .LBB0_31

.LBB0_33:
	s_or_b64 exec, exec, s[0:1]
	s_movk_i32 s0, 0x180
	v_cmp_gt_i32_e32 vcc, s0, v22
	s_and_saveexec_b64 s[4:5], vcc
	s_cbranch_execz .LBB0_41
	v_readlane_b32 s68, v241, 17
	v_readlane_b32 s80, v241, 29
	v_readlane_b32 s81, v241, 30
	s_cmp_lg_u64 s[80:81], 0
	s_cselect_b64 s[0:1], -1, 0
	v_lshl_add_u32 v0, s100, 9, v24
	v_cndmask_b32_e64 v1, 0, 1, s[0:1]
	s_mov_b64 s[6:7], 0
	v_or_b32_e32 v0, v0, v142
	s_lshl_b32 s9, s3, 6
	v_cmp_ne_u32_e64 s[0:1], 1, v1
	s_mov_b32 s8, 0x3e16c740
	v_mov_b32_e32 v1, v22
	v_readlane_b32 s69, v241, 18
	v_readlane_b32 s70, v241, 19
	v_readlane_b32 s71, v241, 20
	v_readlane_b32 s72, v241, 21
	v_readlane_b32 s73, v241, 22
	v_readlane_b32 s74, v241, 23
	v_readlane_b32 s75, v241, 24
	v_readlane_b32 s76, v241, 25
	v_readlane_b32 s77, v241, 26
	v_readlane_b32 s78, v241, 27
	v_readlane_b32 s79, v241, 28
	v_readlane_b32 s82, v241, 31
	v_readlane_b32 s83, v241, 32
	s_branch .LBB0_38

.LBB0_41:
	s_or_b64 exec, exec, s[4:5]
	s_movk_i32 s0, 0x100
	v_cmp_gt_i32_e32 vcc, s0, v22
	s_and_saveexec_b64 s[4:5], vcc
	s_cbranch_execz .LBB0_49
	v_readlane_b32 s36, v241, 33
	v_readlane_b32 s37, v241, 34
	s_cmp_lg_u64 s[36:37], 0
	s_cselect_b64 s[0:1], -1, 0
	v_lshl_add_u32 v0, s100, 9, v24
	v_or_b32_e32 v20, v0, v142
	v_cndmask_b32_e64 v0, 0, 1, s[0:1]
	s_mov_b64 s[6:7], 0
	s_lshl_b32 s10, s3, 6
	v_cmp_ne_u32_e64 s[0:1], 1, v0
	v_mov_b32_e32 v21, v22
	v_readlane_b32 s38, v241, 35
	v_readlane_b32 s39, v241, 36
	v_readlane_b32 s40, v241, 37
	v_readlane_b32 s41, v241, 38
	v_readlane_b32 s42, v241, 39
	v_readlane_b32 s43, v241, 40
	v_readlane_b32 s44, v241, 41
	v_readlane_b32 s45, v241, 42
	v_readlane_b32 s46, v241, 43
	v_readlane_b32 s47, v241, 44
	v_readlane_b32 s48, v241, 45
	v_readlane_b32 s49, v241, 46
	v_readlane_b32 s50, v241, 47
	v_readlane_b32 s51, v241, 48
	s_branch .LBB0_46

.LBB0_49:
	s_or_b64 exec, exec, s[4:5]
	v_cmp_lt_i32_e32 vcc, 63, v22
	s_and_saveexec_b64 s[0:1], vcc
	s_xor_b64 s[0:1], exec, s[0:1]
	s_andn2_saveexec_b64 s[0:1], s[0:1]
	s_cbranch_execz .LBB0_59
	v_lshl_add_u32 v0, s100, 9, v24
	v_or_b32_e32 v2, v0, v142
	s_lshl_b32 s8, s3, 6
	s_mov_b64 s[4:5], 0
	v_mov_b32_e32 v3, v2
	v_mov_b32_e32 v4, v22
	s_branch .LBB0_52

.LBB0_59:
	s_or_b64 exec, exec, s[0:1]
	s_movk_i32 s0, 0x3ff
	v_cmp_lt_i32_e32 vcc, s0, v22
	s_and_saveexec_b64 s[0:1], vcc
	s_xor_b64 s[0:1], exec, s[0:1]
	s_andn2_saveexec_b64 s[0:1], s[0:1]
	s_cbranch_execz .LBB0_71
	v_lshl_add_u32 v0, s100, 9, v24
	v_or_b32_e32 v2, v0, v142
	s_lshl_b32 s8, s3, 6
	s_mov_b64 s[4:5], 0
	v_mov_b32_e32 v3, v2
	v_mov_b32_e32 v4, v22
	s_branch .LBB0_64

.LBB0_71:
	s_or_b64 exec, exec, s[0:1]
	s_movk_i32 s0, 0x7ff
	v_cmp_lt_i32_e32 vcc, s0, v22
	s_and_saveexec_b64 s[0:1], vcc
	s_xor_b64 s[0:1], exec, s[0:1]
	s_lshl_b32 s4, s90, 9
	s_or_saveexec_b64 s[0:1], s[0:1]
	v_mov_b32_e32 v165, s4
	s_xor_b64 exec, exec, s[0:1]
	s_cbranch_execz .LBB0_79
	s_lshl_b32 s8, s90, 9
	s_lshl_b32 s101, s100, 9
	v_lshl_add_u32 v0, v23, 6, s101
	v_or_b32_e32 v2, v0, v142
	s_lshl_b32 s9, s3, 6
	s_mov_b64 s[4:5], 0
	s_branch .LBB0_76
